# v26 with the phase-1 copier stop threshold lowered from 730 to 690 tiles done
# speedup vs baseline: 1.0133x; 1.0133x over previous
.Lcp1_entry:
	v_readfirstlane_b32 s0, v192
	v_lshlrev_b32_e32 v16, 4, v192
	s_add_u32 s4, s38, 0xc7b7100
	s_addc_u32 s5, s39, 0
	s_add_u32 s6, s38, 0xc7b7200
	s_addc_u32 s7, s39, 0
	s_lshr_b32 s0, s0, 6
	s_mov_b32 s1, 0
	s_mov_b32 s30, 2
	v_mov_b32_e32 v93, 0
	v_mov_b32_e32 v94, 1
	v_mov_b32_e32 v95, 16
	v_mov_b32_e32 v96, 20
	v_add_u32_e32 v17, 0x2000, v16
	v_add_u32_e32 v18, 0x4000, v16
	v_add_u32_e32 v19, 0x6000, v16
	v_add_u32_e32 v20, 0x8000, v16
	v_add_u32_e32 v21, 0xa000, v16
	v_add_u32_e32 v22, 0xc000, v16
	v_add_u32_e32 v23, 0xe000, v16
	v_add_u32_e32 v104, 0x10000, v16
	v_add_u32_e32 v105, 0x12000, v16
	v_add_u32_e32 v106, 0x14000, v16
	v_add_u32_e32 v107, 0x16000, v16
	v_add_u32_e32 v108, 0x18000, v16
	v_add_u32_e32 v109, 0x1a000, v16
	v_add_u32_e32 v110, 0x1c000, v16
	v_add_u32_e32 v111, 0x1e000, v16
	s_barrier
	s_cmp_lg_u32 s0, 0
	s_cbranch_scc1 .Lcp1_p0
	s_mov_b64 s[22:23], exec
	s_mov_b64 exec, 1
	global_load_dword v118, v93, s[6:7] sc1
	v_mov_b32_e32 v117, 0xa80
	s_waitcnt vmcnt(0)
	v_readfirstlane_b32 s25, v118
	s_cmpk_gt_u32 s25, 0x2b2
	s_cbranch_scc1 .Lcp1_pnone
	v_mov_b32_e32 v117, 2
	global_atomic_add v117, v93, v117, s[4:5] sc0
	s_waitcnt vmcnt(0)

.Lcp1_ac_A_j:
	s_lshl_b32 s18, s18, 17
	v_add_u32_e32 v92, s24, v16
	s_add_u32 s14, s36, s19
	s_addc_u32 s15, s37, 0
	s_add_u32 s14, s14, s18
	s_addc_u32 s15, s15, 0
	s_add_u32 s12, s12, s18
	s_addc_u32 s13, s13, 0
	s_add_u32 s12, s12, 0x2000
	s_addc_u32 s13, s13, 0
	global_load_dwordx4 v[180:183], v16, s[12:13] nt
	global_load_dwordx4 v[184:187], v17, s[12:13] nt
	global_load_dwordx4 v[188:191], v18, s[12:13] nt
	global_load_dwordx4 v[196:199], v19, s[12:13] nt
	global_load_dwordx4 v[200:203], v20, s[12:13] nt
	global_load_dwordx4 v[204:207], v21, s[12:13] nt
	global_load_dwordx4 v[208:211], v22, s[12:13] nt
	global_load_dwordx4 v[212:215], v23, s[12:13] nt
	global_load_dwordx4 v[216:219], v104, s[12:13] nt
	global_load_dwordx4 v[220:223], v105, s[12:13] nt
	global_load_dwordx4 v[224:227], v106, s[12:13] nt
	global_load_dwordx4 v[228:231], v107, s[12:13] nt
	global_load_dwordx4 v[244:247], v108, s[12:13] nt
	global_load_dwordx4 v[248:251], v109, s[12:13] nt
	global_load_dwordx4 v[4:7], v110, s[12:13] nt
	global_load_dwordx4 v[8:11], v92, s[12:13] nt
	s_waitcnt vmcnt(31)
	global_store_dwordx4 v16, v[30:33], s[10:11] nt
	s_waitcnt vmcnt(31)
	global_store_dwordx4 v17, v[34:37], s[10:11] nt
	s_waitcnt vmcnt(31)
	global_store_dwordx4 v18, v[38:41], s[10:11] nt
	s_waitcnt vmcnt(31)
	global_store_dwordx4 v19, v[42:45], s[10:11] nt
	s_waitcnt vmcnt(31)
	global_store_dwordx4 v20, v[46:49], s[10:11] nt
	s_waitcnt vmcnt(31)
	global_store_dwordx4 v21, v[50:53], s[10:11] nt
	s_waitcnt vmcnt(31)
	global_store_dwordx4 v22, v[54:57], s[10:11] nt
	s_waitcnt vmcnt(31)
	global_store_dwordx4 v23, v[58:61], s[10:11] nt
	s_waitcnt vmcnt(31)
	global_store_dwordx4 v104, v[62:65], s[10:11] nt
	s_waitcnt vmcnt(31)
	global_store_dwordx4 v105, v[66:69], s[10:11] nt
	s_waitcnt vmcnt(31)
	global_store_dwordx4 v106, v[70:73], s[10:11] nt
	s_waitcnt vmcnt(31)
	global_store_dwordx4 v107, v[74:77], s[10:11] nt
	s_waitcnt vmcnt(31)
	global_store_dwordx4 v108, v[164:167], s[10:11] nt
	s_waitcnt vmcnt(31)
	global_store_dwordx4 v109, v[168:171], s[10:11] nt
	s_waitcnt vmcnt(31)
	global_store_dwordx4 v110, v[172:175], s[10:11] nt
	s_waitcnt vmcnt(31)
	global_store_dwordx4 v91, v[176:179], s[10:11] nt
	s_cmp_lg_u32 s0, 0
	s_cbranch_scc1 .Lcp1_A_s4
	s_mov_b64 s[22:23], exec
	s_mov_b64 exec, 1
	s_cmp_lg_u32 s1, 0
	s_cbranch_scc1 .Lcp1_A_s4stop
	s_waitcnt vmcnt(32)
	v_readfirstlane_b32 s25, v118
	s_cmpk_gt_u32 s25, 0x2b2
	s_cselect_b32 s1, 1, 0
	v_readfirstlane_b32 s26, v117
	s_cmpk_ge_u32 s26, 0xa80
	s_cselect_b32 s27, 1, 0
	s_or_b32 s1, s1, s27
	s_branch .Lcp1_A_s4pub

.Lcp1_ac_B_j:
	s_lshl_b32 s18, s18, 17
	v_add_u32_e32 v91, s24, v16
	s_add_u32 s10, s36, s19
	s_addc_u32 s11, s37, 0
	s_add_u32 s10, s10, s18
	s_addc_u32 s11, s11, 0
	s_add_u32 s8, s8, s18
	s_addc_u32 s9, s9, 0
	s_add_u32 s8, s8, 0x2000
	s_addc_u32 s9, s9, 0
	global_load_dwordx4 v[30:33], v16, s[8:9] nt
	global_load_dwordx4 v[34:37], v17, s[8:9] nt
	global_load_dwordx4 v[38:41], v18, s[8:9] nt
	global_load_dwordx4 v[42:45], v19, s[8:9] nt
	global_load_dwordx4 v[46:49], v20, s[8:9] nt
	global_load_dwordx4 v[50:53], v21, s[8:9] nt
	global_load_dwordx4 v[54:57], v22, s[8:9] nt
	global_load_dwordx4 v[58:61], v23, s[8:9] nt
	global_load_dwordx4 v[62:65], v104, s[8:9] nt
	global_load_dwordx4 v[66:69], v105, s[8:9] nt
	global_load_dwordx4 v[70:73], v106, s[8:9] nt
	global_load_dwordx4 v[74:77], v107, s[8:9] nt
	global_load_dwordx4 v[164:167], v108, s[8:9] nt
	global_load_dwordx4 v[168:171], v109, s[8:9] nt
	global_load_dwordx4 v[172:175], v110, s[8:9] nt
	global_load_dwordx4 v[176:179], v91, s[8:9] nt
	s_waitcnt vmcnt(31)
	global_store_dwordx4 v16, v[180:183], s[14:15] nt
	s_waitcnt vmcnt(31)
	global_store_dwordx4 v17, v[184:187], s[14:15] nt
	s_waitcnt vmcnt(31)
	global_store_dwordx4 v18, v[188:191], s[14:15] nt
	s_waitcnt vmcnt(31)
	global_store_dwordx4 v19, v[196:199], s[14:15] nt
	s_waitcnt vmcnt(31)
	global_store_dwordx4 v20, v[200:203], s[14:15] nt
	s_waitcnt vmcnt(31)
	global_store_dwordx4 v21, v[204:207], s[14:15] nt
	s_waitcnt vmcnt(31)
	global_store_dwordx4 v22, v[208:211], s[14:15] nt
	s_waitcnt vmcnt(31)
	global_store_dwordx4 v23, v[212:215], s[14:15] nt
	s_waitcnt vmcnt(31)
	global_store_dwordx4 v104, v[216:219], s[14:15] nt
	s_waitcnt vmcnt(31)
	global_store_dwordx4 v105, v[220:223], s[14:15] nt
	s_waitcnt vmcnt(31)
	global_store_dwordx4 v106, v[224:227], s[14:15] nt
	s_waitcnt vmcnt(31)
	global_store_dwordx4 v107, v[228:231], s[14:15] nt
	s_waitcnt vmcnt(31)
	global_store_dwordx4 v108, v[244:247], s[14:15] nt
	s_waitcnt vmcnt(31)
	global_store_dwordx4 v109, v[248:251], s[14:15] nt
	s_waitcnt vmcnt(31)
	global_store_dwordx4 v110, v[4:7], s[14:15] nt
	s_waitcnt vmcnt(31)
	global_store_dwordx4 v92, v[8:11], s[14:15] nt
	s_cmp_lg_u32 s0, 0
	s_cbranch_scc1 .Lcp1_B_s4
	s_mov_b64 s[22:23], exec
	s_mov_b64 exec, 1
	s_cmp_lg_u32 s1, 0
	s_cbranch_scc1 .Lcp1_B_s4stop
	s_waitcnt vmcnt(32)
	v_readfirstlane_b32 s25, v118
	s_cmpk_gt_u32 s25, 0x2b2
	s_cselect_b32 s1, 1, 0
	v_readfirstlane_b32 s26, v117
	s_cmpk_ge_u32 s26, 0xa80
	s_cselect_b32 s27, 1, 0
	s_or_b32 s1, s1, s27
	s_branch .Lcp1_B_s4pub
